# scan waves run at s_setprio 2 inside the chunk loop
# baseline (speedup 1.0000x reference)
.LBB0_649:
	s_and_b64 vcc, exec, s[0:1]
	s_cbranch_vccz .LBB0_676
	s_cmpk_lt_u32 s3, 0x100
	s_mov_b64 s[0:1], -1
	s_cbranch_scc0 .LBB0_654
	v_lshrrev_b32_e32 v1, 4, v152
	v_lshl_or_b32 v1, s50, 2, v1
	v_and_b32_e32 v118, 15, v153
	v_lshlrev_b32_e32 v6, 4, v118
	v_mov_b32_e32 v7, 0
	v_lshlrev_b32_e32 v8, 2, v1
	v_add_u32_e32 v8, 0x9300, v8
	v_add_u32_e32 v120, 0x400, v8
	v_lshlrev_b32_e32 v9, 6, v1
	v_lshl_add_u32 v9, v118, 2, v9
	v_add_u32_e32 v9, 0x9b00, v9
	v_mov_b32_e32 v2, 0
	v_mov_b32_e32 v3, 0
	v_mov_b32_e32 v4, 0
	v_mov_b32_e32 v5, 0
	s_mov_b32 s0, 0
	s_mov_b32 s1, 0x11b00
	s_waitcnt vmcnt(0) lgkmcnt(0)
	s_setprio 2
	s_barrier
.LBB0_652:
	ds_read_b128 v[20:23], v6 offset:0
	ds_read_b128 v[28:31], v6 offset:512
	ds_read_b128 v[24:27], v6 offset:256
	ds_read_b128 v[32:35], v6 offset:768
	ds_read_b128 v[56:59], v7 offset:36864
	ds_read_b128 v[36:39], v6 offset:1024
	ds_read_b128 v[40:43], v6 offset:1280
	ds_read2_b32 v[64:65], v8 offset0:0 offset1:16
	ds_read_b128 v[48:51], v6 offset:1792
	ds_read_b128 v[44:47], v6 offset:1536
	ds_read_b128 v[52:55], v6 offset:2048
	ds_read_b128 v[60:63], v7 offset:36880
	s_waitcnt lgkmcnt(11)
	v_pk_mul_f32 v[10:11], v[2:3], v[20:21] op_sel_hi:[0,1]
	ds_read_b128 v[68:71], v6 offset:2304
	s_waitcnt lgkmcnt(10)
	v_pk_mul_f32 v[14:15], v[2:3], v[24:25] op_sel_hi:[0,1]
	v_pk_fma_f32 v[10:11], v[2:3], v[22:23], v[10:11] op_sel:[1,0,0] op_sel_hi:[1,1,1]
	v_pk_fma_f32 v[14:15], v[2:3], v[26:27], v[14:15] op_sel:[1,0,0] op_sel_hi:[1,1,1]
	ds_read_b128 v[76:79], v6 offset:2816
	v_pk_fma_f32 v[10:11], v[4:5], v[28:29], v[10:11] op_sel_hi:[0,1,1]
	s_waitcnt lgkmcnt(10)
	v_pk_fma_f32 v[14:15], v[4:5], v[32:33], v[14:15] op_sel_hi:[0,1,1]
	v_pk_fma_f32 v[10:11], v[4:5], v[30:31], v[10:11] op_sel:[1,0,0] op_sel_hi:[1,1,1]
	ds_read_b128 v[72:75], v6 offset:2560
	v_pk_fma_f32 v[14:15], v[4:5], v[34:35], v[14:15] op_sel:[1,0,0] op_sel_hi:[1,1,1]
	s_waitcnt lgkmcnt(10)
	v_fma_f32 v12, -v56, v10, v11
	s_waitcnt lgkmcnt(9)
	v_pk_mul_f32 v[114:115], v[2:3], v[36:37]
	ds_read_b128 v[80:83], v6 offset:3072
	v_add_f32_dpp v10, v10, v10 row_ror:8 row_mask:0xf bank_mask:0xf bound_ctrl:1
	v_add_f32_dpp v12, v12, v12 row_ror:8 row_mask:0xf bank_mask:0xf bound_ctrl:1
	v_pk_mul_f32 v[116:117], v[4:5], v[38:39]
	ds_read_b128 v[104:107], v7 offset:36912
	v_add_f32_dpp v10, v10, v10 row_ror:4 row_mask:0xf bank_mask:0xf bound_ctrl:1
	v_add_f32_dpp v12, v12, v12 row_ror:4 row_mask:0xf bank_mask:0xf bound_ctrl:1
	s_waitcnt lgkmcnt(9)
	v_pk_fma_f32 v[114:115], v[40:41], v[64:65], v[114:115] op_sel_hi:[1,0,1]
	ds_read_b128 v[84:87], v6 offset:3328
	v_add_f32_dpp v10, v10, v10 row_ror:2 row_mask:0xf bank_mask:0xf bound_ctrl:1
	v_add_f32_dpp v12, v12, v12 row_ror:2 row_mask:0xf bank_mask:0xf bound_ctrl:1
	v_pk_fma_f32 v[116:117], v[42:43], v[64:65], v[116:117] op_sel_hi:[1,0,1]
	ds_read_b128 v[88:91], v6 offset:3584
	v_add_f32_dpp v10, v10, v10 row_ror:1 row_mask:0xf bank_mask:0xf bound_ctrl:1
	v_add_f32_dpp v12, v12, v12 row_ror:1 row_mask:0xf bank_mask:0xf bound_ctrl:1
	v_fmac_f32_e32 v14, v64, v59
	ds_read2_b32 v[112:113], v8 offset0:32 offset1:48
	s_waitcnt lgkmcnt(8)
	v_pk_fma_f32 v[114:115], v[48:49], v[64:65], v[114:115] op_sel:[0,1,0] op_sel_hi:[1,1,1]
	v_fmac_f32_e32 v12, v64, v57
	v_pk_fma_f32 v[116:117], v[50:51], v[64:65], v[116:117] op_sel:[0,1,0] op_sel_hi:[1,1,1]
	ds_read_b128 v[96:99], v6 offset:4096
	v_fmac_f32_e32 v15, v64, v61
	v_pk_fma_f32 v[114:115], v[44:45], v[10:11], v[114:115] op_sel_hi:[1,0,1] neg_lo:[1,0,0] neg_hi:[1,0,0]
	v_fmac_f32_e32 v15, v65, v63
	ds_read_b128 v[92:95], v6 offset:3840
	v_pk_fma_f32 v[116:117], v[46:47], v[10:11], v[116:117] op_sel_hi:[1,0,1] neg_lo:[1,0,0] neg_hi:[1,0,0]
	v_fma_f32 v14, -v10, v58, v14
	v_fma_f32 v15, -v10, v60, v15
	ds_read_b128 v[100:103], v6 offset:4352
	v_fma_f32 v15, -v12, v62, v15
	v_pk_fma_f32 v[2:3], v[52:53], v[12:13], v[114:115] op_sel_hi:[1,0,1] neg_lo:[1,0,0] neg_hi:[1,0,0]
	v_pk_fma_f32 v[4:5], v[54:55], v[12:13], v[116:117] op_sel_hi:[1,0,1] neg_lo:[1,0,0] neg_hi:[1,0,0]
	ds_read_b128 v[108:111], v7 offset:36928
	ds_write2st64_b32 v9, v14, v15 offset0:0 offset1:4
	s_waitcnt lgkmcnt(8)
	v_pk_mul_f32 v[10:11], v[2:3], v[68:69] op_sel_hi:[0,1]
	ds_read_b128 v[20:23], v6 offset:4608
	v_pk_mul_f32 v[14:15], v[2:3], v[72:73] op_sel_hi:[0,1]
	v_pk_fma_f32 v[10:11], v[2:3], v[70:71], v[10:11] op_sel:[1,0,0] op_sel_hi:[1,1,1]
	v_pk_fma_f32 v[14:15], v[2:3], v[74:75], v[14:15] op_sel:[1,0,0] op_sel_hi:[1,1,1]
	ds_read_b128 v[28:31], v6 offset:5120
	v_pk_fma_f32 v[10:11], v[4:5], v[76:77], v[10:11] op_sel_hi:[0,1,1]
	v_pk_fma_f32 v[14:15], v[4:5], v[80:81], v[14:15] op_sel_hi:[0,1,1]
	v_pk_fma_f32 v[10:11], v[4:5], v[78:79], v[10:11] op_sel:[1,0,0] op_sel_hi:[1,1,1]
	ds_read_b128 v[24:27], v6 offset:4864
	v_pk_fma_f32 v[14:15], v[4:5], v[82:83], v[14:15] op_sel:[1,0,0] op_sel_hi:[1,1,1]
	v_fma_f32 v12, -v104, v10, v11
	s_waitcnt lgkmcnt(10)
	v_pk_mul_f32 v[114:115], v[2:3], v[84:85]
	ds_read_b128 v[32:35], v6 offset:5376
	v_add_f32_dpp v10, v10, v10 row_ror:8 row_mask:0xf bank_mask:0xf bound_ctrl:1
	v_add_f32_dpp v12, v12, v12 row_ror:8 row_mask:0xf bank_mask:0xf bound_ctrl:1
	v_pk_mul_f32 v[116:117], v[4:5], v[86:87]
	ds_read_b128 v[56:59], v7 offset:36960
	v_add_f32_dpp v10, v10, v10 row_ror:4 row_mask:0xf bank_mask:0xf bound_ctrl:1
	v_add_f32_dpp v12, v12, v12 row_ror:4 row_mask:0xf bank_mask:0xf bound_ctrl:1
	s_waitcnt lgkmcnt(10)
	v_pk_fma_f32 v[114:115], v[88:89], v[112:113], v[114:115] op_sel_hi:[1,0,1]
	ds_read_b128 v[36:39], v6 offset:5632
	v_add_f32_dpp v10, v10, v10 row_ror:2 row_mask:0xf bank_mask:0xf bound_ctrl:1
	v_add_f32_dpp v12, v12, v12 row_ror:2 row_mask:0xf bank_mask:0xf bound_ctrl:1
	v_pk_fma_f32 v[116:117], v[90:91], v[112:113], v[116:117] op_sel_hi:[1,0,1]
	ds_read_b128 v[40:43], v6 offset:5888
	v_add_f32_dpp v10, v10, v10 row_ror:1 row_mask:0xf bank_mask:0xf bound_ctrl:1
	v_add_f32_dpp v12, v12, v12 row_ror:1 row_mask:0xf bank_mask:0xf bound_ctrl:1
	v_fmac_f32_e32 v14, v112, v107
	ds_read2_b32 v[64:65], v8 offset0:64 offset1:80
	s_waitcnt lgkmcnt(9)
	v_pk_fma_f32 v[114:115], v[96:97], v[112:113], v[114:115] op_sel:[0,1,0] op_sel_hi:[1,1,1]
	v_fmac_f32_e32 v12, v112, v105
	v_pk_fma_f32 v[116:117], v[98:99], v[112:113], v[116:117] op_sel:[0,1,0] op_sel_hi:[1,1,1]
	ds_read_b128 v[48:51], v6 offset:6400
	v_fmac_f32_e32 v15, v112, v109
	v_pk_fma_f32 v[114:115], v[92:93], v[10:11], v[114:115] op_sel_hi:[1,0,1] neg_lo:[1,0,0] neg_hi:[1,0,0]
	v_fmac_f32_e32 v15, v113, v111
	ds_read_b128 v[44:47], v6 offset:6144
	v_pk_fma_f32 v[116:117], v[94:95], v[10:11], v[116:117] op_sel_hi:[1,0,1] neg_lo:[1,0,0] neg_hi:[1,0,0]
	v_fma_f32 v14, -v10, v106, v14
	v_fma_f32 v15, -v10, v108, v15
	ds_read_b128 v[52:55], v6 offset:6656
	v_fma_f32 v15, -v12, v110, v15
	v_pk_fma_f32 v[2:3], v[100:101], v[12:13], v[114:115] op_sel_hi:[1,0,1] neg_lo:[1,0,0] neg_hi:[1,0,0]
	v_pk_fma_f32 v[4:5], v[102:103], v[12:13], v[116:117] op_sel_hi:[1,0,1] neg_lo:[1,0,0] neg_hi:[1,0,0]
	ds_read_b128 v[60:63], v7 offset:36976
	ds_write2st64_b32 v9, v14, v15 offset0:8 offset1:12
	s_waitcnt lgkmcnt(8)
	v_pk_mul_f32 v[10:11], v[2:3], v[20:21] op_sel_hi:[0,1]
	ds_read_b128 v[68:71], v6 offset:6912
	v_pk_mul_f32 v[14:15], v[2:3], v[24:25] op_sel_hi:[0,1]
	v_pk_fma_f32 v[10:11], v[2:3], v[22:23], v[10:11] op_sel:[1,0,0] op_sel_hi:[1,1,1]
	v_pk_fma_f32 v[14:15], v[2:3], v[26:27], v[14:15] op_sel:[1,0,0] op_sel_hi:[1,1,1]
	ds_read_b128 v[76:79], v6 offset:7424
	v_pk_fma_f32 v[10:11], v[4:5], v[28:29], v[10:11] op_sel_hi:[0,1,1]
	v_pk_fma_f32 v[14:15], v[4:5], v[32:33], v[14:15] op_sel_hi:[0,1,1]
	v_pk_fma_f32 v[10:11], v[4:5], v[30:31], v[10:11] op_sel:[1,0,0] op_sel_hi:[1,1,1]
	ds_read_b128 v[72:75], v6 offset:7168
	v_pk_fma_f32 v[14:15], v[4:5], v[34:35], v[14:15] op_sel:[1,0,0] op_sel_hi:[1,1,1]
	v_fma_f32 v12, -v56, v10, v11
	s_waitcnt lgkmcnt(10)
	v_pk_mul_f32 v[114:115], v[2:3], v[36:37]
	ds_read_b128 v[80:83], v6 offset:7680
	v_add_f32_dpp v10, v10, v10 row_ror:8 row_mask:0xf bank_mask:0xf bound_ctrl:1
	v_add_f32_dpp v12, v12, v12 row_ror:8 row_mask:0xf bank_mask:0xf bound_ctrl:1
	v_pk_mul_f32 v[116:117], v[4:5], v[38:39]
	ds_read_b128 v[104:107], v7 offset:37008
	v_add_f32_dpp v10, v10, v10 row_ror:4 row_mask:0xf bank_mask:0xf bound_ctrl:1
	v_add_f32_dpp v12, v12, v12 row_ror:4 row_mask:0xf bank_mask:0xf bound_ctrl:1
	s_waitcnt lgkmcnt(10)
	v_pk_fma_f32 v[114:115], v[40:41], v[64:65], v[114:115] op_sel_hi:[1,0,1]
	ds_read_b128 v[84:87], v6 offset:7936
	v_add_f32_dpp v10, v10, v10 row_ror:2 row_mask:0xf bank_mask:0xf bound_ctrl:1
	v_add_f32_dpp v12, v12, v12 row_ror:2 row_mask:0xf bank_mask:0xf bound_ctrl:1
	v_pk_fma_f32 v[116:117], v[42:43], v[64:65], v[116:117] op_sel_hi:[1,0,1]
	ds_read_b128 v[88:91], v6 offset:8192
	v_add_f32_dpp v10, v10, v10 row_ror:1 row_mask:0xf bank_mask:0xf bound_ctrl:1
	v_add_f32_dpp v12, v12, v12 row_ror:1 row_mask:0xf bank_mask:0xf bound_ctrl:1
	v_fmac_f32_e32 v14, v64, v59
	ds_read2_b32 v[112:113], v8 offset0:96 offset1:112
	s_waitcnt lgkmcnt(9)
	v_pk_fma_f32 v[114:115], v[48:49], v[64:65], v[114:115] op_sel:[0,1,0] op_sel_hi:[1,1,1]
	v_fmac_f32_e32 v12, v64, v57
	v_pk_fma_f32 v[116:117], v[50:51], v[64:65], v[116:117] op_sel:[0,1,0] op_sel_hi:[1,1,1]
	ds_read_b128 v[96:99], v6 offset:8704
	v_fmac_f32_e32 v15, v64, v61
	v_pk_fma_f32 v[114:115], v[44:45], v[10:11], v[114:115] op_sel_hi:[1,0,1] neg_lo:[1,0,0] neg_hi:[1,0,0]
	v_fmac_f32_e32 v15, v65, v63
	ds_read_b128 v[92:95], v6 offset:8448
	v_pk_fma_f32 v[116:117], v[46:47], v[10:11], v[116:117] op_sel_hi:[1,0,1] neg_lo:[1,0,0] neg_hi:[1,0,0]
	v_fma_f32 v14, -v10, v58, v14
	v_fma_f32 v15, -v10, v60, v15
	ds_read_b128 v[100:103], v6 offset:8960
	v_fma_f32 v15, -v12, v62, v15
	v_pk_fma_f32 v[2:3], v[52:53], v[12:13], v[114:115] op_sel_hi:[1,0,1] neg_lo:[1,0,0] neg_hi:[1,0,0]
	v_pk_fma_f32 v[4:5], v[54:55], v[12:13], v[116:117] op_sel_hi:[1,0,1] neg_lo:[1,0,0] neg_hi:[1,0,0]
	ds_read_b128 v[108:111], v7 offset:37024
	ds_write2st64_b32 v9, v14, v15 offset0:16 offset1:20
	s_waitcnt lgkmcnt(8)
	v_pk_mul_f32 v[10:11], v[2:3], v[68:69] op_sel_hi:[0,1]
	ds_read_b128 v[20:23], v6 offset:9216
	v_pk_mul_f32 v[14:15], v[2:3], v[72:73] op_sel_hi:[0,1]
	v_pk_fma_f32 v[10:11], v[2:3], v[70:71], v[10:11] op_sel:[1,0,0] op_sel_hi:[1,1,1]
	v_pk_fma_f32 v[14:15], v[2:3], v[74:75], v[14:15] op_sel:[1,0,0] op_sel_hi:[1,1,1]
	ds_read_b128 v[28:31], v6 offset:9728
	v_pk_fma_f32 v[10:11], v[4:5], v[76:77], v[10:11] op_sel_hi:[0,1,1]
	v_pk_fma_f32 v[14:15], v[4:5], v[80:81], v[14:15] op_sel_hi:[0,1,1]
	v_pk_fma_f32 v[10:11], v[4:5], v[78:79], v[10:11] op_sel:[1,0,0] op_sel_hi:[1,1,1]
	ds_read_b128 v[24:27], v6 offset:9472
	v_pk_fma_f32 v[14:15], v[4:5], v[82:83], v[14:15] op_sel:[1,0,0] op_sel_hi:[1,1,1]
	v_fma_f32 v12, -v104, v10, v11
	s_waitcnt lgkmcnt(10)
	v_pk_mul_f32 v[114:115], v[2:3], v[84:85]
	ds_read_b128 v[32:35], v6 offset:9984
	v_add_f32_dpp v10, v10, v10 row_ror:8 row_mask:0xf bank_mask:0xf bound_ctrl:1
	v_add_f32_dpp v12, v12, v12 row_ror:8 row_mask:0xf bank_mask:0xf bound_ctrl:1
	v_pk_mul_f32 v[116:117], v[4:5], v[86:87]
	ds_read_b128 v[56:59], v7 offset:37056
	v_add_f32_dpp v10, v10, v10 row_ror:4 row_mask:0xf bank_mask:0xf bound_ctrl:1
	v_add_f32_dpp v12, v12, v12 row_ror:4 row_mask:0xf bank_mask:0xf bound_ctrl:1
	s_waitcnt lgkmcnt(10)
	v_pk_fma_f32 v[114:115], v[88:89], v[112:113], v[114:115] op_sel_hi:[1,0,1]
	ds_read_b128 v[36:39], v6 offset:10240
	v_add_f32_dpp v10, v10, v10 row_ror:2 row_mask:0xf bank_mask:0xf bound_ctrl:1
	v_add_f32_dpp v12, v12, v12 row_ror:2 row_mask:0xf bank_mask:0xf bound_ctrl:1
	v_pk_fma_f32 v[116:117], v[90:91], v[112:113], v[116:117] op_sel_hi:[1,0,1]
	ds_read_b128 v[40:43], v6 offset:10496
	v_add_f32_dpp v10, v10, v10 row_ror:1 row_mask:0xf bank_mask:0xf bound_ctrl:1
	v_add_f32_dpp v12, v12, v12 row_ror:1 row_mask:0xf bank_mask:0xf bound_ctrl:1
	v_fmac_f32_e32 v14, v112, v107
	ds_read2_b32 v[64:65], v8 offset0:128 offset1:144
	s_waitcnt lgkmcnt(9)
	v_pk_fma_f32 v[114:115], v[96:97], v[112:113], v[114:115] op_sel:[0,1,0] op_sel_hi:[1,1,1]
	v_fmac_f32_e32 v12, v112, v105
	v_pk_fma_f32 v[116:117], v[98:99], v[112:113], v[116:117] op_sel:[0,1,0] op_sel_hi:[1,1,1]
	ds_read_b128 v[48:51], v6 offset:11008
	v_fmac_f32_e32 v15, v112, v109
	v_pk_fma_f32 v[114:115], v[92:93], v[10:11], v[114:115] op_sel_hi:[1,0,1] neg_lo:[1,0,0] neg_hi:[1,0,0]
	v_fmac_f32_e32 v15, v113, v111
	ds_read_b128 v[44:47], v6 offset:10752
	v_pk_fma_f32 v[116:117], v[94:95], v[10:11], v[116:117] op_sel_hi:[1,0,1] neg_lo:[1,0,0] neg_hi:[1,0,0]
	v_fma_f32 v14, -v10, v106, v14
	v_fma_f32 v15, -v10, v108, v15
	ds_read_b128 v[52:55], v6 offset:11264
	v_fma_f32 v15, -v12, v110, v15
	v_pk_fma_f32 v[2:3], v[100:101], v[12:13], v[114:115] op_sel_hi:[1,0,1] neg_lo:[1,0,0] neg_hi:[1,0,0]
	v_pk_fma_f32 v[4:5], v[102:103], v[12:13], v[116:117] op_sel_hi:[1,0,1] neg_lo:[1,0,0] neg_hi:[1,0,0]
	ds_read_b128 v[60:63], v7 offset:37072
	ds_write2st64_b32 v9, v14, v15 offset0:24 offset1:28
	s_waitcnt lgkmcnt(8)
	v_pk_mul_f32 v[10:11], v[2:3], v[20:21] op_sel_hi:[0,1]
	ds_read_b128 v[68:71], v6 offset:11520
	v_pk_mul_f32 v[14:15], v[2:3], v[24:25] op_sel_hi:[0,1]
	v_pk_fma_f32 v[10:11], v[2:3], v[22:23], v[10:11] op_sel:[1,0,0] op_sel_hi:[1,1,1]
	v_pk_fma_f32 v[14:15], v[2:3], v[26:27], v[14:15] op_sel:[1,0,0] op_sel_hi:[1,1,1]
	ds_read_b128 v[76:79], v6 offset:12032
	v_pk_fma_f32 v[10:11], v[4:5], v[28:29], v[10:11] op_sel_hi:[0,1,1]
	v_pk_fma_f32 v[14:15], v[4:5], v[32:33], v[14:15] op_sel_hi:[0,1,1]
	v_pk_fma_f32 v[10:11], v[4:5], v[30:31], v[10:11] op_sel:[1,0,0] op_sel_hi:[1,1,1]
	ds_read_b128 v[72:75], v6 offset:11776
	v_pk_fma_f32 v[14:15], v[4:5], v[34:35], v[14:15] op_sel:[1,0,0] op_sel_hi:[1,1,1]
	v_fma_f32 v12, -v56, v10, v11
	s_waitcnt lgkmcnt(10)
	v_pk_mul_f32 v[114:115], v[2:3], v[36:37]
	ds_read_b128 v[80:83], v6 offset:12288
	v_add_f32_dpp v10, v10, v10 row_ror:8 row_mask:0xf bank_mask:0xf bound_ctrl:1
	v_add_f32_dpp v12, v12, v12 row_ror:8 row_mask:0xf bank_mask:0xf bound_ctrl:1
	v_pk_mul_f32 v[116:117], v[4:5], v[38:39]
	ds_read_b128 v[104:107], v7 offset:37104
	v_add_f32_dpp v10, v10, v10 row_ror:4 row_mask:0xf bank_mask:0xf bound_ctrl:1
	v_add_f32_dpp v12, v12, v12 row_ror:4 row_mask:0xf bank_mask:0xf bound_ctrl:1
	s_waitcnt lgkmcnt(10)
	v_pk_fma_f32 v[114:115], v[40:41], v[64:65], v[114:115] op_sel_hi:[1,0,1]
	ds_read_b128 v[84:87], v6 offset:12544
	v_add_f32_dpp v10, v10, v10 row_ror:2 row_mask:0xf bank_mask:0xf bound_ctrl:1
	v_add_f32_dpp v12, v12, v12 row_ror:2 row_mask:0xf bank_mask:0xf bound_ctrl:1
	v_pk_fma_f32 v[116:117], v[42:43], v[64:65], v[116:117] op_sel_hi:[1,0,1]
	ds_read_b128 v[88:91], v6 offset:12800
	v_add_f32_dpp v10, v10, v10 row_ror:1 row_mask:0xf bank_mask:0xf bound_ctrl:1
	v_add_f32_dpp v12, v12, v12 row_ror:1 row_mask:0xf bank_mask:0xf bound_ctrl:1
	v_fmac_f32_e32 v14, v64, v59
	ds_read2_b32 v[112:113], v8 offset0:160 offset1:176
	s_waitcnt lgkmcnt(9)
	v_pk_fma_f32 v[114:115], v[48:49], v[64:65], v[114:115] op_sel:[0,1,0] op_sel_hi:[1,1,1]
	v_fmac_f32_e32 v12, v64, v57
	v_pk_fma_f32 v[116:117], v[50:51], v[64:65], v[116:117] op_sel:[0,1,0] op_sel_hi:[1,1,1]
	ds_read_b128 v[96:99], v6 offset:13312
	v_fmac_f32_e32 v15, v64, v61
	v_pk_fma_f32 v[114:115], v[44:45], v[10:11], v[114:115] op_sel_hi:[1,0,1] neg_lo:[1,0,0] neg_hi:[1,0,0]
	v_fmac_f32_e32 v15, v65, v63
	ds_read_b128 v[92:95], v6 offset:13056
	v_pk_fma_f32 v[116:117], v[46:47], v[10:11], v[116:117] op_sel_hi:[1,0,1] neg_lo:[1,0,0] neg_hi:[1,0,0]
	v_fma_f32 v14, -v10, v58, v14
	v_fma_f32 v15, -v10, v60, v15
	ds_read_b128 v[100:103], v6 offset:13568
	v_fma_f32 v15, -v12, v62, v15
	v_pk_fma_f32 v[2:3], v[52:53], v[12:13], v[114:115] op_sel_hi:[1,0,1] neg_lo:[1,0,0] neg_hi:[1,0,0]
	v_pk_fma_f32 v[4:5], v[54:55], v[12:13], v[116:117] op_sel_hi:[1,0,1] neg_lo:[1,0,0] neg_hi:[1,0,0]
	ds_read_b128 v[108:111], v7 offset:37120
	ds_write2st64_b32 v9, v14, v15 offset0:32 offset1:36
	s_waitcnt lgkmcnt(8)
	v_pk_mul_f32 v[10:11], v[2:3], v[68:69] op_sel_hi:[0,1]
	ds_read_b128 v[20:23], v6 offset:13824
	v_pk_mul_f32 v[14:15], v[2:3], v[72:73] op_sel_hi:[0,1]
	v_pk_fma_f32 v[10:11], v[2:3], v[70:71], v[10:11] op_sel:[1,0,0] op_sel_hi:[1,1,1]
	v_pk_fma_f32 v[14:15], v[2:3], v[74:75], v[14:15] op_sel:[1,0,0] op_sel_hi:[1,1,1]
	ds_read_b128 v[28:31], v6 offset:14336
	v_pk_fma_f32 v[10:11], v[4:5], v[76:77], v[10:11] op_sel_hi:[0,1,1]
	v_pk_fma_f32 v[14:15], v[4:5], v[80:81], v[14:15] op_sel_hi:[0,1,1]
	v_pk_fma_f32 v[10:11], v[4:5], v[78:79], v[10:11] op_sel:[1,0,0] op_sel_hi:[1,1,1]
	ds_read_b128 v[24:27], v6 offset:14080
	v_pk_fma_f32 v[14:15], v[4:5], v[82:83], v[14:15] op_sel:[1,0,0] op_sel_hi:[1,1,1]
	v_fma_f32 v12, -v104, v10, v11
	s_waitcnt lgkmcnt(10)
	v_pk_mul_f32 v[114:115], v[2:3], v[84:85]
	ds_read_b128 v[32:35], v6 offset:14592
	v_add_f32_dpp v10, v10, v10 row_ror:8 row_mask:0xf bank_mask:0xf bound_ctrl:1
	v_add_f32_dpp v12, v12, v12 row_ror:8 row_mask:0xf bank_mask:0xf bound_ctrl:1
	v_pk_mul_f32 v[116:117], v[4:5], v[86:87]
	ds_read_b128 v[56:59], v7 offset:37152
	v_add_f32_dpp v10, v10, v10 row_ror:4 row_mask:0xf bank_mask:0xf bound_ctrl:1
	v_add_f32_dpp v12, v12, v12 row_ror:4 row_mask:0xf bank_mask:0xf bound_ctrl:1
	s_waitcnt lgkmcnt(10)
	v_pk_fma_f32 v[114:115], v[88:89], v[112:113], v[114:115] op_sel_hi:[1,0,1]
	ds_read_b128 v[36:39], v6 offset:14848
	v_add_f32_dpp v10, v10, v10 row_ror:2 row_mask:0xf bank_mask:0xf bound_ctrl:1
	v_add_f32_dpp v12, v12, v12 row_ror:2 row_mask:0xf bank_mask:0xf bound_ctrl:1
	v_pk_fma_f32 v[116:117], v[90:91], v[112:113], v[116:117] op_sel_hi:[1,0,1]
	ds_read_b128 v[40:43], v6 offset:15104
	v_add_f32_dpp v10, v10, v10 row_ror:1 row_mask:0xf bank_mask:0xf bound_ctrl:1
	v_add_f32_dpp v12, v12, v12 row_ror:1 row_mask:0xf bank_mask:0xf bound_ctrl:1
	v_fmac_f32_e32 v14, v112, v107
	ds_read2_b32 v[64:65], v8 offset0:192 offset1:208
	s_waitcnt lgkmcnt(9)
	v_pk_fma_f32 v[114:115], v[96:97], v[112:113], v[114:115] op_sel:[0,1,0] op_sel_hi:[1,1,1]
	v_fmac_f32_e32 v12, v112, v105
	v_pk_fma_f32 v[116:117], v[98:99], v[112:113], v[116:117] op_sel:[0,1,0] op_sel_hi:[1,1,1]
	ds_read_b128 v[48:51], v6 offset:15616
	v_fmac_f32_e32 v15, v112, v109
	v_pk_fma_f32 v[114:115], v[92:93], v[10:11], v[114:115] op_sel_hi:[1,0,1] neg_lo:[1,0,0] neg_hi:[1,0,0]
	v_fmac_f32_e32 v15, v113, v111
	ds_read_b128 v[44:47], v6 offset:15360
	v_pk_fma_f32 v[116:117], v[94:95], v[10:11], v[116:117] op_sel_hi:[1,0,1] neg_lo:[1,0,0] neg_hi:[1,0,0]
	v_fma_f32 v14, -v10, v106, v14
	v_fma_f32 v15, -v10, v108, v15
	ds_read_b128 v[52:55], v6 offset:15872
	v_fma_f32 v15, -v12, v110, v15
	v_pk_fma_f32 v[2:3], v[100:101], v[12:13], v[114:115] op_sel_hi:[1,0,1] neg_lo:[1,0,0] neg_hi:[1,0,0]
	v_pk_fma_f32 v[4:5], v[102:103], v[12:13], v[116:117] op_sel_hi:[1,0,1] neg_lo:[1,0,0] neg_hi:[1,0,0]
	ds_read_b128 v[60:63], v7 offset:37168
	ds_write2st64_b32 v9, v14, v15 offset0:40 offset1:44
	s_waitcnt lgkmcnt(8)
	v_pk_mul_f32 v[10:11], v[2:3], v[20:21] op_sel_hi:[0,1]
	ds_read_b128 v[68:71], v6 offset:16128
	v_pk_mul_f32 v[14:15], v[2:3], v[24:25] op_sel_hi:[0,1]
	v_pk_fma_f32 v[10:11], v[2:3], v[22:23], v[10:11] op_sel:[1,0,0] op_sel_hi:[1,1,1]
	v_pk_fma_f32 v[14:15], v[2:3], v[26:27], v[14:15] op_sel:[1,0,0] op_sel_hi:[1,1,1]
	ds_read_b128 v[76:79], v6 offset:16640
	v_pk_fma_f32 v[10:11], v[4:5], v[28:29], v[10:11] op_sel_hi:[0,1,1]
	v_pk_fma_f32 v[14:15], v[4:5], v[32:33], v[14:15] op_sel_hi:[0,1,1]
	v_pk_fma_f32 v[10:11], v[4:5], v[30:31], v[10:11] op_sel:[1,0,0] op_sel_hi:[1,1,1]
	ds_read_b128 v[72:75], v6 offset:16384
	v_pk_fma_f32 v[14:15], v[4:5], v[34:35], v[14:15] op_sel:[1,0,0] op_sel_hi:[1,1,1]
	v_fma_f32 v12, -v56, v10, v11
	s_waitcnt lgkmcnt(10)
	v_pk_mul_f32 v[114:115], v[2:3], v[36:37]
	ds_read_b128 v[80:83], v6 offset:16896
	v_add_f32_dpp v10, v10, v10 row_ror:8 row_mask:0xf bank_mask:0xf bound_ctrl:1
	v_add_f32_dpp v12, v12, v12 row_ror:8 row_mask:0xf bank_mask:0xf bound_ctrl:1
	v_pk_mul_f32 v[116:117], v[4:5], v[38:39]
	ds_read_b128 v[104:107], v7 offset:37200
	v_add_f32_dpp v10, v10, v10 row_ror:4 row_mask:0xf bank_mask:0xf bound_ctrl:1
	v_add_f32_dpp v12, v12, v12 row_ror:4 row_mask:0xf bank_mask:0xf bound_ctrl:1
	s_waitcnt lgkmcnt(10)
	v_pk_fma_f32 v[114:115], v[40:41], v[64:65], v[114:115] op_sel_hi:[1,0,1]
	ds_read_b128 v[84:87], v6 offset:17152
	v_add_f32_dpp v10, v10, v10 row_ror:2 row_mask:0xf bank_mask:0xf bound_ctrl:1
	v_add_f32_dpp v12, v12, v12 row_ror:2 row_mask:0xf bank_mask:0xf bound_ctrl:1
	v_pk_fma_f32 v[116:117], v[42:43], v[64:65], v[116:117] op_sel_hi:[1,0,1]
	ds_read_b128 v[88:91], v6 offset:17408
	v_add_f32_dpp v10, v10, v10 row_ror:1 row_mask:0xf bank_mask:0xf bound_ctrl:1
	v_add_f32_dpp v12, v12, v12 row_ror:1 row_mask:0xf bank_mask:0xf bound_ctrl:1
	v_fmac_f32_e32 v14, v64, v59
	ds_read2_b32 v[112:113], v8 offset0:224 offset1:240
	s_waitcnt lgkmcnt(9)
	v_pk_fma_f32 v[114:115], v[48:49], v[64:65], v[114:115] op_sel:[0,1,0] op_sel_hi:[1,1,1]
	v_fmac_f32_e32 v12, v64, v57
	v_pk_fma_f32 v[116:117], v[50:51], v[64:65], v[116:117] op_sel:[0,1,0] op_sel_hi:[1,1,1]
	ds_read_b128 v[96:99], v6 offset:17920
	v_fmac_f32_e32 v15, v64, v61
	v_pk_fma_f32 v[114:115], v[44:45], v[10:11], v[114:115] op_sel_hi:[1,0,1] neg_lo:[1,0,0] neg_hi:[1,0,0]
	v_fmac_f32_e32 v15, v65, v63
	ds_read_b128 v[92:95], v6 offset:17664
	v_pk_fma_f32 v[116:117], v[46:47], v[10:11], v[116:117] op_sel_hi:[1,0,1] neg_lo:[1,0,0] neg_hi:[1,0,0]
	v_fma_f32 v14, -v10, v58, v14
	v_fma_f32 v15, -v10, v60, v15
	ds_read_b128 v[100:103], v6 offset:18176
	v_fma_f32 v15, -v12, v62, v15
	v_pk_fma_f32 v[2:3], v[52:53], v[12:13], v[114:115] op_sel_hi:[1,0,1] neg_lo:[1,0,0] neg_hi:[1,0,0]
	v_pk_fma_f32 v[4:5], v[54:55], v[12:13], v[116:117] op_sel_hi:[1,0,1] neg_lo:[1,0,0] neg_hi:[1,0,0]
	ds_read_b128 v[108:111], v7 offset:37216
	ds_write2st64_b32 v9, v14, v15 offset0:48 offset1:52
	s_waitcnt lgkmcnt(8)
	v_pk_mul_f32 v[10:11], v[2:3], v[68:69] op_sel_hi:[0,1]
	ds_read_b128 v[20:23], v6 offset:18432
	v_pk_mul_f32 v[14:15], v[2:3], v[72:73] op_sel_hi:[0,1]
	v_pk_fma_f32 v[10:11], v[2:3], v[70:71], v[10:11] op_sel:[1,0,0] op_sel_hi:[1,1,1]
	v_pk_fma_f32 v[14:15], v[2:3], v[74:75], v[14:15] op_sel:[1,0,0] op_sel_hi:[1,1,1]
	ds_read_b128 v[28:31], v6 offset:18944
	v_pk_fma_f32 v[10:11], v[4:5], v[76:77], v[10:11] op_sel_hi:[0,1,1]
	v_pk_fma_f32 v[14:15], v[4:5], v[80:81], v[14:15] op_sel_hi:[0,1,1]
	v_pk_fma_f32 v[10:11], v[4:5], v[78:79], v[10:11] op_sel:[1,0,0] op_sel_hi:[1,1,1]
	ds_read_b128 v[24:27], v6 offset:18688
	v_pk_fma_f32 v[14:15], v[4:5], v[82:83], v[14:15] op_sel:[1,0,0] op_sel_hi:[1,1,1]
	v_fma_f32 v12, -v104, v10, v11
	s_waitcnt lgkmcnt(10)
	v_pk_mul_f32 v[114:115], v[2:3], v[84:85]
	ds_read_b128 v[32:35], v6 offset:19200
	v_add_f32_dpp v10, v10, v10 row_ror:8 row_mask:0xf bank_mask:0xf bound_ctrl:1
	v_add_f32_dpp v12, v12, v12 row_ror:8 row_mask:0xf bank_mask:0xf bound_ctrl:1
	v_pk_mul_f32 v[116:117], v[4:5], v[86:87]
	ds_read_b128 v[56:59], v7 offset:37248
	v_add_f32_dpp v10, v10, v10 row_ror:4 row_mask:0xf bank_mask:0xf bound_ctrl:1
	v_add_f32_dpp v12, v12, v12 row_ror:4 row_mask:0xf bank_mask:0xf bound_ctrl:1
	s_waitcnt lgkmcnt(10)
	v_pk_fma_f32 v[114:115], v[88:89], v[112:113], v[114:115] op_sel_hi:[1,0,1]
	ds_read_b128 v[36:39], v6 offset:19456
	v_add_f32_dpp v10, v10, v10 row_ror:2 row_mask:0xf bank_mask:0xf bound_ctrl:1
	v_add_f32_dpp v12, v12, v12 row_ror:2 row_mask:0xf bank_mask:0xf bound_ctrl:1
	v_pk_fma_f32 v[116:117], v[90:91], v[112:113], v[116:117] op_sel_hi:[1,0,1]
	ds_read_b128 v[40:43], v6 offset:19712
	v_add_f32_dpp v10, v10, v10 row_ror:1 row_mask:0xf bank_mask:0xf bound_ctrl:1
	v_add_f32_dpp v12, v12, v12 row_ror:1 row_mask:0xf bank_mask:0xf bound_ctrl:1
	v_fmac_f32_e32 v14, v112, v107
	ds_read2_b32 v[64:65], v120 offset0:0 offset1:16
	s_waitcnt lgkmcnt(9)
	v_pk_fma_f32 v[114:115], v[96:97], v[112:113], v[114:115] op_sel:[0,1,0] op_sel_hi:[1,1,1]
	v_fmac_f32_e32 v12, v112, v105
	v_pk_fma_f32 v[116:117], v[98:99], v[112:113], v[116:117] op_sel:[0,1,0] op_sel_hi:[1,1,1]
	ds_read_b128 v[48:51], v6 offset:20224
	v_fmac_f32_e32 v15, v112, v109
	v_pk_fma_f32 v[114:115], v[92:93], v[10:11], v[114:115] op_sel_hi:[1,0,1] neg_lo:[1,0,0] neg_hi:[1,0,0]
	v_fmac_f32_e32 v15, v113, v111
	ds_read_b128 v[44:47], v6 offset:19968
	v_pk_fma_f32 v[116:117], v[94:95], v[10:11], v[116:117] op_sel_hi:[1,0,1] neg_lo:[1,0,0] neg_hi:[1,0,0]
	v_fma_f32 v14, -v10, v106, v14
	v_fma_f32 v15, -v10, v108, v15
	ds_read_b128 v[52:55], v6 offset:20480
	v_fma_f32 v15, -v12, v110, v15
	v_pk_fma_f32 v[2:3], v[100:101], v[12:13], v[114:115] op_sel_hi:[1,0,1] neg_lo:[1,0,0] neg_hi:[1,0,0]
	v_pk_fma_f32 v[4:5], v[102:103], v[12:13], v[116:117] op_sel_hi:[1,0,1] neg_lo:[1,0,0] neg_hi:[1,0,0]
	ds_read_b128 v[60:63], v7 offset:37264
	ds_write2st64_b32 v9, v14, v15 offset0:56 offset1:60
	s_waitcnt lgkmcnt(8)
	v_pk_mul_f32 v[10:11], v[2:3], v[20:21] op_sel_hi:[0,1]
	ds_read_b128 v[68:71], v6 offset:20736
	v_pk_mul_f32 v[14:15], v[2:3], v[24:25] op_sel_hi:[0,1]
	v_pk_fma_f32 v[10:11], v[2:3], v[22:23], v[10:11] op_sel:[1,0,0] op_sel_hi:[1,1,1]
	v_pk_fma_f32 v[14:15], v[2:3], v[26:27], v[14:15] op_sel:[1,0,0] op_sel_hi:[1,1,1]
	ds_read_b128 v[76:79], v6 offset:21248
	v_pk_fma_f32 v[10:11], v[4:5], v[28:29], v[10:11] op_sel_hi:[0,1,1]
	v_pk_fma_f32 v[14:15], v[4:5], v[32:33], v[14:15] op_sel_hi:[0,1,1]
	v_pk_fma_f32 v[10:11], v[4:5], v[30:31], v[10:11] op_sel:[1,0,0] op_sel_hi:[1,1,1]
	ds_read_b128 v[72:75], v6 offset:20992
	v_pk_fma_f32 v[14:15], v[4:5], v[34:35], v[14:15] op_sel:[1,0,0] op_sel_hi:[1,1,1]
	v_fma_f32 v12, -v56, v10, v11
	s_waitcnt lgkmcnt(10)
	v_pk_mul_f32 v[114:115], v[2:3], v[36:37]
	ds_read_b128 v[80:83], v6 offset:21504
	v_add_f32_dpp v10, v10, v10 row_ror:8 row_mask:0xf bank_mask:0xf bound_ctrl:1
	v_add_f32_dpp v12, v12, v12 row_ror:8 row_mask:0xf bank_mask:0xf bound_ctrl:1
	v_pk_mul_f32 v[116:117], v[4:5], v[38:39]
	ds_read_b128 v[104:107], v7 offset:37296
	v_add_f32_dpp v10, v10, v10 row_ror:4 row_mask:0xf bank_mask:0xf bound_ctrl:1
	v_add_f32_dpp v12, v12, v12 row_ror:4 row_mask:0xf bank_mask:0xf bound_ctrl:1
	s_waitcnt lgkmcnt(10)
	v_pk_fma_f32 v[114:115], v[40:41], v[64:65], v[114:115] op_sel_hi:[1,0,1]
	ds_read_b128 v[84:87], v6 offset:21760
	v_add_f32_dpp v10, v10, v10 row_ror:2 row_mask:0xf bank_mask:0xf bound_ctrl:1
	v_add_f32_dpp v12, v12, v12 row_ror:2 row_mask:0xf bank_mask:0xf bound_ctrl:1
	v_pk_fma_f32 v[116:117], v[42:43], v[64:65], v[116:117] op_sel_hi:[1,0,1]
	ds_read_b128 v[88:91], v6 offset:22016
	v_add_f32_dpp v10, v10, v10 row_ror:1 row_mask:0xf bank_mask:0xf bound_ctrl:1
	v_add_f32_dpp v12, v12, v12 row_ror:1 row_mask:0xf bank_mask:0xf bound_ctrl:1
	v_fmac_f32_e32 v14, v64, v59
	ds_read2_b32 v[112:113], v120 offset0:32 offset1:48
	s_waitcnt lgkmcnt(9)
	v_pk_fma_f32 v[114:115], v[48:49], v[64:65], v[114:115] op_sel:[0,1,0] op_sel_hi:[1,1,1]
	v_fmac_f32_e32 v12, v64, v57
	v_pk_fma_f32 v[116:117], v[50:51], v[64:65], v[116:117] op_sel:[0,1,0] op_sel_hi:[1,1,1]
	ds_read_b128 v[96:99], v6 offset:22528
	v_fmac_f32_e32 v15, v64, v61
	v_pk_fma_f32 v[114:115], v[44:45], v[10:11], v[114:115] op_sel_hi:[1,0,1] neg_lo:[1,0,0] neg_hi:[1,0,0]
	v_fmac_f32_e32 v15, v65, v63
	ds_read_b128 v[92:95], v6 offset:22272
	v_pk_fma_f32 v[116:117], v[46:47], v[10:11], v[116:117] op_sel_hi:[1,0,1] neg_lo:[1,0,0] neg_hi:[1,0,0]
	v_fma_f32 v14, -v10, v58, v14
	v_fma_f32 v15, -v10, v60, v15
	ds_read_b128 v[100:103], v6 offset:22784
	v_fma_f32 v15, -v12, v62, v15
	v_pk_fma_f32 v[2:3], v[52:53], v[12:13], v[114:115] op_sel_hi:[1,0,1] neg_lo:[1,0,0] neg_hi:[1,0,0]
	v_pk_fma_f32 v[4:5], v[54:55], v[12:13], v[116:117] op_sel_hi:[1,0,1] neg_lo:[1,0,0] neg_hi:[1,0,0]
	ds_read_b128 v[108:111], v7 offset:37312
	ds_write2st64_b32 v9, v14, v15 offset0:64 offset1:68
	s_waitcnt lgkmcnt(8)
	v_pk_mul_f32 v[10:11], v[2:3], v[68:69] op_sel_hi:[0,1]
	ds_read_b128 v[20:23], v6 offset:23040
	v_pk_mul_f32 v[14:15], v[2:3], v[72:73] op_sel_hi:[0,1]
	v_pk_fma_f32 v[10:11], v[2:3], v[70:71], v[10:11] op_sel:[1,0,0] op_sel_hi:[1,1,1]
	v_pk_fma_f32 v[14:15], v[2:3], v[74:75], v[14:15] op_sel:[1,0,0] op_sel_hi:[1,1,1]
	ds_read_b128 v[28:31], v6 offset:23552
	v_pk_fma_f32 v[10:11], v[4:5], v[76:77], v[10:11] op_sel_hi:[0,1,1]
	v_pk_fma_f32 v[14:15], v[4:5], v[80:81], v[14:15] op_sel_hi:[0,1,1]
	v_pk_fma_f32 v[10:11], v[4:5], v[78:79], v[10:11] op_sel:[1,0,0] op_sel_hi:[1,1,1]
	ds_read_b128 v[24:27], v6 offset:23296
	v_pk_fma_f32 v[14:15], v[4:5], v[82:83], v[14:15] op_sel:[1,0,0] op_sel_hi:[1,1,1]
	v_fma_f32 v12, -v104, v10, v11
	s_waitcnt lgkmcnt(10)
	v_pk_mul_f32 v[114:115], v[2:3], v[84:85]
	ds_read_b128 v[32:35], v6 offset:23808
	v_add_f32_dpp v10, v10, v10 row_ror:8 row_mask:0xf bank_mask:0xf bound_ctrl:1
	v_add_f32_dpp v12, v12, v12 row_ror:8 row_mask:0xf bank_mask:0xf bound_ctrl:1
	v_pk_mul_f32 v[116:117], v[4:5], v[86:87]
	ds_read_b128 v[56:59], v7 offset:37344
	v_add_f32_dpp v10, v10, v10 row_ror:4 row_mask:0xf bank_mask:0xf bound_ctrl:1
	v_add_f32_dpp v12, v12, v12 row_ror:4 row_mask:0xf bank_mask:0xf bound_ctrl:1
	s_waitcnt lgkmcnt(10)
	v_pk_fma_f32 v[114:115], v[88:89], v[112:113], v[114:115] op_sel_hi:[1,0,1]
	ds_read_b128 v[36:39], v6 offset:24064
	v_add_f32_dpp v10, v10, v10 row_ror:2 row_mask:0xf bank_mask:0xf bound_ctrl:1
	v_add_f32_dpp v12, v12, v12 row_ror:2 row_mask:0xf bank_mask:0xf bound_ctrl:1
	v_pk_fma_f32 v[116:117], v[90:91], v[112:113], v[116:117] op_sel_hi:[1,0,1]
	ds_read_b128 v[40:43], v6 offset:24320
	v_add_f32_dpp v10, v10, v10 row_ror:1 row_mask:0xf bank_mask:0xf bound_ctrl:1
	v_add_f32_dpp v12, v12, v12 row_ror:1 row_mask:0xf bank_mask:0xf bound_ctrl:1
	v_fmac_f32_e32 v14, v112, v107
	ds_read2_b32 v[64:65], v120 offset0:64 offset1:80
	s_waitcnt lgkmcnt(9)
	v_pk_fma_f32 v[114:115], v[96:97], v[112:113], v[114:115] op_sel:[0,1,0] op_sel_hi:[1,1,1]
	v_fmac_f32_e32 v12, v112, v105
	v_pk_fma_f32 v[116:117], v[98:99], v[112:113], v[116:117] op_sel:[0,1,0] op_sel_hi:[1,1,1]
	ds_read_b128 v[48:51], v6 offset:24832
	v_fmac_f32_e32 v15, v112, v109
	v_pk_fma_f32 v[114:115], v[92:93], v[10:11], v[114:115] op_sel_hi:[1,0,1] neg_lo:[1,0,0] neg_hi:[1,0,0]
	v_fmac_f32_e32 v15, v113, v111
	ds_read_b128 v[44:47], v6 offset:24576
	v_pk_fma_f32 v[116:117], v[94:95], v[10:11], v[116:117] op_sel_hi:[1,0,1] neg_lo:[1,0,0] neg_hi:[1,0,0]
	v_fma_f32 v14, -v10, v106, v14
	v_fma_f32 v15, -v10, v108, v15
	ds_read_b128 v[52:55], v6 offset:25088
	v_fma_f32 v15, -v12, v110, v15
	v_pk_fma_f32 v[2:3], v[100:101], v[12:13], v[114:115] op_sel_hi:[1,0,1] neg_lo:[1,0,0] neg_hi:[1,0,0]
	v_pk_fma_f32 v[4:5], v[102:103], v[12:13], v[116:117] op_sel_hi:[1,0,1] neg_lo:[1,0,0] neg_hi:[1,0,0]
	ds_read_b128 v[60:63], v7 offset:37360
	ds_write2st64_b32 v9, v14, v15 offset0:72 offset1:76
	s_waitcnt lgkmcnt(8)
	v_pk_mul_f32 v[10:11], v[2:3], v[20:21] op_sel_hi:[0,1]
	ds_read_b128 v[68:71], v6 offset:25344
	v_pk_mul_f32 v[14:15], v[2:3], v[24:25] op_sel_hi:[0,1]
	v_pk_fma_f32 v[10:11], v[2:3], v[22:23], v[10:11] op_sel:[1,0,0] op_sel_hi:[1,1,1]
	v_pk_fma_f32 v[14:15], v[2:3], v[26:27], v[14:15] op_sel:[1,0,0] op_sel_hi:[1,1,1]
	ds_read_b128 v[76:79], v6 offset:25856
	v_pk_fma_f32 v[10:11], v[4:5], v[28:29], v[10:11] op_sel_hi:[0,1,1]
	v_pk_fma_f32 v[14:15], v[4:5], v[32:33], v[14:15] op_sel_hi:[0,1,1]
	v_pk_fma_f32 v[10:11], v[4:5], v[30:31], v[10:11] op_sel:[1,0,0] op_sel_hi:[1,1,1]
	ds_read_b128 v[72:75], v6 offset:25600
	v_pk_fma_f32 v[14:15], v[4:5], v[34:35], v[14:15] op_sel:[1,0,0] op_sel_hi:[1,1,1]
	v_fma_f32 v12, -v56, v10, v11
	s_waitcnt lgkmcnt(10)
	v_pk_mul_f32 v[114:115], v[2:3], v[36:37]
	ds_read_b128 v[80:83], v6 offset:26112
	v_add_f32_dpp v10, v10, v10 row_ror:8 row_mask:0xf bank_mask:0xf bound_ctrl:1
	v_add_f32_dpp v12, v12, v12 row_ror:8 row_mask:0xf bank_mask:0xf bound_ctrl:1
	v_pk_mul_f32 v[116:117], v[4:5], v[38:39]
	ds_read_b128 v[104:107], v7 offset:37392
	v_add_f32_dpp v10, v10, v10 row_ror:4 row_mask:0xf bank_mask:0xf bound_ctrl:1
	v_add_f32_dpp v12, v12, v12 row_ror:4 row_mask:0xf bank_mask:0xf bound_ctrl:1
	s_waitcnt lgkmcnt(10)
	v_pk_fma_f32 v[114:115], v[40:41], v[64:65], v[114:115] op_sel_hi:[1,0,1]
	ds_read_b128 v[84:87], v6 offset:26368
	v_add_f32_dpp v10, v10, v10 row_ror:2 row_mask:0xf bank_mask:0xf bound_ctrl:1
	v_add_f32_dpp v12, v12, v12 row_ror:2 row_mask:0xf bank_mask:0xf bound_ctrl:1
	v_pk_fma_f32 v[116:117], v[42:43], v[64:65], v[116:117] op_sel_hi:[1,0,1]
	ds_read_b128 v[88:91], v6 offset:26624
	v_add_f32_dpp v10, v10, v10 row_ror:1 row_mask:0xf bank_mask:0xf bound_ctrl:1
	v_add_f32_dpp v12, v12, v12 row_ror:1 row_mask:0xf bank_mask:0xf bound_ctrl:1
	v_fmac_f32_e32 v14, v64, v59
	ds_read2_b32 v[112:113], v120 offset0:96 offset1:112
	s_waitcnt lgkmcnt(9)
	v_pk_fma_f32 v[114:115], v[48:49], v[64:65], v[114:115] op_sel:[0,1,0] op_sel_hi:[1,1,1]
	v_fmac_f32_e32 v12, v64, v57
	v_pk_fma_f32 v[116:117], v[50:51], v[64:65], v[116:117] op_sel:[0,1,0] op_sel_hi:[1,1,1]
	ds_read_b128 v[96:99], v6 offset:27136
	v_fmac_f32_e32 v15, v64, v61
	v_pk_fma_f32 v[114:115], v[44:45], v[10:11], v[114:115] op_sel_hi:[1,0,1] neg_lo:[1,0,0] neg_hi:[1,0,0]
	v_fmac_f32_e32 v15, v65, v63
	ds_read_b128 v[92:95], v6 offset:26880
	v_pk_fma_f32 v[116:117], v[46:47], v[10:11], v[116:117] op_sel_hi:[1,0,1] neg_lo:[1,0,0] neg_hi:[1,0,0]
	v_fma_f32 v14, -v10, v58, v14
	v_fma_f32 v15, -v10, v60, v15
	ds_read_b128 v[100:103], v6 offset:27392
	v_fma_f32 v15, -v12, v62, v15
	v_pk_fma_f32 v[2:3], v[52:53], v[12:13], v[114:115] op_sel_hi:[1,0,1] neg_lo:[1,0,0] neg_hi:[1,0,0]
	v_pk_fma_f32 v[4:5], v[54:55], v[12:13], v[116:117] op_sel_hi:[1,0,1] neg_lo:[1,0,0] neg_hi:[1,0,0]
	ds_read_b128 v[108:111], v7 offset:37408
	ds_write2st64_b32 v9, v14, v15 offset0:80 offset1:84
	s_waitcnt lgkmcnt(8)
	v_pk_mul_f32 v[10:11], v[2:3], v[68:69] op_sel_hi:[0,1]
	ds_read_b128 v[20:23], v6 offset:27648
	v_pk_mul_f32 v[14:15], v[2:3], v[72:73] op_sel_hi:[0,1]
	v_pk_fma_f32 v[10:11], v[2:3], v[70:71], v[10:11] op_sel:[1,0,0] op_sel_hi:[1,1,1]
	v_pk_fma_f32 v[14:15], v[2:3], v[74:75], v[14:15] op_sel:[1,0,0] op_sel_hi:[1,1,1]
	ds_read_b128 v[28:31], v6 offset:28160
	v_pk_fma_f32 v[10:11], v[4:5], v[76:77], v[10:11] op_sel_hi:[0,1,1]
	v_pk_fma_f32 v[14:15], v[4:5], v[80:81], v[14:15] op_sel_hi:[0,1,1]
	v_pk_fma_f32 v[10:11], v[4:5], v[78:79], v[10:11] op_sel:[1,0,0] op_sel_hi:[1,1,1]
	ds_read_b128 v[24:27], v6 offset:27904
	v_pk_fma_f32 v[14:15], v[4:5], v[82:83], v[14:15] op_sel:[1,0,0] op_sel_hi:[1,1,1]
	v_fma_f32 v12, -v104, v10, v11
	s_waitcnt lgkmcnt(10)
	v_pk_mul_f32 v[114:115], v[2:3], v[84:85]
	ds_read_b128 v[32:35], v6 offset:28416
	v_add_f32_dpp v10, v10, v10 row_ror:8 row_mask:0xf bank_mask:0xf bound_ctrl:1
	v_add_f32_dpp v12, v12, v12 row_ror:8 row_mask:0xf bank_mask:0xf bound_ctrl:1
	v_pk_mul_f32 v[116:117], v[4:5], v[86:87]
	ds_read_b128 v[56:59], v7 offset:37440
	v_add_f32_dpp v10, v10, v10 row_ror:4 row_mask:0xf bank_mask:0xf bound_ctrl:1
	v_add_f32_dpp v12, v12, v12 row_ror:4 row_mask:0xf bank_mask:0xf bound_ctrl:1
	s_waitcnt lgkmcnt(10)
	v_pk_fma_f32 v[114:115], v[88:89], v[112:113], v[114:115] op_sel_hi:[1,0,1]
	ds_read_b128 v[36:39], v6 offset:28672
	v_add_f32_dpp v10, v10, v10 row_ror:2 row_mask:0xf bank_mask:0xf bound_ctrl:1
	v_add_f32_dpp v12, v12, v12 row_ror:2 row_mask:0xf bank_mask:0xf bound_ctrl:1
	v_pk_fma_f32 v[116:117], v[90:91], v[112:113], v[116:117] op_sel_hi:[1,0,1]
	ds_read_b128 v[40:43], v6 offset:28928
	v_add_f32_dpp v10, v10, v10 row_ror:1 row_mask:0xf bank_mask:0xf bound_ctrl:1
	v_add_f32_dpp v12, v12, v12 row_ror:1 row_mask:0xf bank_mask:0xf bound_ctrl:1
	v_fmac_f32_e32 v14, v112, v107
	ds_read2_b32 v[64:65], v120 offset0:128 offset1:144
	s_waitcnt lgkmcnt(9)
	v_pk_fma_f32 v[114:115], v[96:97], v[112:113], v[114:115] op_sel:[0,1,0] op_sel_hi:[1,1,1]
	v_fmac_f32_e32 v12, v112, v105
	v_pk_fma_f32 v[116:117], v[98:99], v[112:113], v[116:117] op_sel:[0,1,0] op_sel_hi:[1,1,1]
	ds_read_b128 v[48:51], v6 offset:29440
	v_fmac_f32_e32 v15, v112, v109
	v_pk_fma_f32 v[114:115], v[92:93], v[10:11], v[114:115] op_sel_hi:[1,0,1] neg_lo:[1,0,0] neg_hi:[1,0,0]
	v_fmac_f32_e32 v15, v113, v111
	ds_read_b128 v[44:47], v6 offset:29184
	v_pk_fma_f32 v[116:117], v[94:95], v[10:11], v[116:117] op_sel_hi:[1,0,1] neg_lo:[1,0,0] neg_hi:[1,0,0]
	v_fma_f32 v14, -v10, v106, v14
	v_fma_f32 v15, -v10, v108, v15
	ds_read_b128 v[52:55], v6 offset:29696
	v_fma_f32 v15, -v12, v110, v15
	v_pk_fma_f32 v[2:3], v[100:101], v[12:13], v[114:115] op_sel_hi:[1,0,1] neg_lo:[1,0,0] neg_hi:[1,0,0]
	v_pk_fma_f32 v[4:5], v[102:103], v[12:13], v[116:117] op_sel_hi:[1,0,1] neg_lo:[1,0,0] neg_hi:[1,0,0]
	ds_read_b128 v[60:63], v7 offset:37456
	ds_write2st64_b32 v9, v14, v15 offset0:88 offset1:92
	s_waitcnt lgkmcnt(8)
	v_pk_mul_f32 v[10:11], v[2:3], v[20:21] op_sel_hi:[0,1]
	ds_read_b128 v[68:71], v6 offset:29952
	v_pk_mul_f32 v[14:15], v[2:3], v[24:25] op_sel_hi:[0,1]
	v_pk_fma_f32 v[10:11], v[2:3], v[22:23], v[10:11] op_sel:[1,0,0] op_sel_hi:[1,1,1]
	v_pk_fma_f32 v[14:15], v[2:3], v[26:27], v[14:15] op_sel:[1,0,0] op_sel_hi:[1,1,1]
	ds_read_b128 v[76:79], v6 offset:30464
	v_pk_fma_f32 v[10:11], v[4:5], v[28:29], v[10:11] op_sel_hi:[0,1,1]
	v_pk_fma_f32 v[14:15], v[4:5], v[32:33], v[14:15] op_sel_hi:[0,1,1]
	v_pk_fma_f32 v[10:11], v[4:5], v[30:31], v[10:11] op_sel:[1,0,0] op_sel_hi:[1,1,1]
	ds_read_b128 v[72:75], v6 offset:30208
	v_pk_fma_f32 v[14:15], v[4:5], v[34:35], v[14:15] op_sel:[1,0,0] op_sel_hi:[1,1,1]
	v_fma_f32 v12, -v56, v10, v11
	s_waitcnt lgkmcnt(10)
	v_pk_mul_f32 v[114:115], v[2:3], v[36:37]
	ds_read_b128 v[80:83], v6 offset:30720
	v_add_f32_dpp v10, v10, v10 row_ror:8 row_mask:0xf bank_mask:0xf bound_ctrl:1
	v_add_f32_dpp v12, v12, v12 row_ror:8 row_mask:0xf bank_mask:0xf bound_ctrl:1
	v_pk_mul_f32 v[116:117], v[4:5], v[38:39]
	ds_read_b128 v[104:107], v7 offset:37488
	v_add_f32_dpp v10, v10, v10 row_ror:4 row_mask:0xf bank_mask:0xf bound_ctrl:1
	v_add_f32_dpp v12, v12, v12 row_ror:4 row_mask:0xf bank_mask:0xf bound_ctrl:1
	s_waitcnt lgkmcnt(10)
	v_pk_fma_f32 v[114:115], v[40:41], v[64:65], v[114:115] op_sel_hi:[1,0,1]
	ds_read_b128 v[84:87], v6 offset:30976
	v_add_f32_dpp v10, v10, v10 row_ror:2 row_mask:0xf bank_mask:0xf bound_ctrl:1
	v_add_f32_dpp v12, v12, v12 row_ror:2 row_mask:0xf bank_mask:0xf bound_ctrl:1
	v_pk_fma_f32 v[116:117], v[42:43], v[64:65], v[116:117] op_sel_hi:[1,0,1]
	ds_read_b128 v[88:91], v6 offset:31232
	v_add_f32_dpp v10, v10, v10 row_ror:1 row_mask:0xf bank_mask:0xf bound_ctrl:1
	v_add_f32_dpp v12, v12, v12 row_ror:1 row_mask:0xf bank_mask:0xf bound_ctrl:1
	v_fmac_f32_e32 v14, v64, v59
	ds_read2_b32 v[112:113], v120 offset0:160 offset1:176
	s_waitcnt lgkmcnt(9)
	v_pk_fma_f32 v[114:115], v[48:49], v[64:65], v[114:115] op_sel:[0,1,0] op_sel_hi:[1,1,1]
	v_fmac_f32_e32 v12, v64, v57
	v_pk_fma_f32 v[116:117], v[50:51], v[64:65], v[116:117] op_sel:[0,1,0] op_sel_hi:[1,1,1]
	ds_read_b128 v[96:99], v6 offset:31744
	v_fmac_f32_e32 v15, v64, v61
	v_pk_fma_f32 v[114:115], v[44:45], v[10:11], v[114:115] op_sel_hi:[1,0,1] neg_lo:[1,0,0] neg_hi:[1,0,0]
	v_fmac_f32_e32 v15, v65, v63
	ds_read_b128 v[92:95], v6 offset:31488
	v_pk_fma_f32 v[116:117], v[46:47], v[10:11], v[116:117] op_sel_hi:[1,0,1] neg_lo:[1,0,0] neg_hi:[1,0,0]
	v_fma_f32 v14, -v10, v58, v14
	v_fma_f32 v15, -v10, v60, v15
	ds_read_b128 v[100:103], v6 offset:32000
	v_fma_f32 v15, -v12, v62, v15
	v_pk_fma_f32 v[2:3], v[52:53], v[12:13], v[114:115] op_sel_hi:[1,0,1] neg_lo:[1,0,0] neg_hi:[1,0,0]
	v_pk_fma_f32 v[4:5], v[54:55], v[12:13], v[116:117] op_sel_hi:[1,0,1] neg_lo:[1,0,0] neg_hi:[1,0,0]
	ds_read_b128 v[108:111], v7 offset:37504
	ds_write2st64_b32 v9, v14, v15 offset0:96 offset1:100
	s_waitcnt lgkmcnt(8)
	v_pk_mul_f32 v[10:11], v[2:3], v[68:69] op_sel_hi:[0,1]
	ds_read_b128 v[20:23], v6 offset:32256
	v_pk_mul_f32 v[14:15], v[2:3], v[72:73] op_sel_hi:[0,1]
	v_pk_fma_f32 v[10:11], v[2:3], v[70:71], v[10:11] op_sel:[1,0,0] op_sel_hi:[1,1,1]
	v_pk_fma_f32 v[14:15], v[2:3], v[74:75], v[14:15] op_sel:[1,0,0] op_sel_hi:[1,1,1]
	ds_read_b128 v[28:31], v6 offset:32768
	v_pk_fma_f32 v[10:11], v[4:5], v[76:77], v[10:11] op_sel_hi:[0,1,1]
	v_pk_fma_f32 v[14:15], v[4:5], v[80:81], v[14:15] op_sel_hi:[0,1,1]
	v_pk_fma_f32 v[10:11], v[4:5], v[78:79], v[10:11] op_sel:[1,0,0] op_sel_hi:[1,1,1]
	ds_read_b128 v[24:27], v6 offset:32512
	v_pk_fma_f32 v[14:15], v[4:5], v[82:83], v[14:15] op_sel:[1,0,0] op_sel_hi:[1,1,1]
	v_fma_f32 v12, -v104, v10, v11
	s_waitcnt lgkmcnt(10)
	v_pk_mul_f32 v[114:115], v[2:3], v[84:85]
	ds_read_b128 v[32:35], v6 offset:33024
	v_add_f32_dpp v10, v10, v10 row_ror:8 row_mask:0xf bank_mask:0xf bound_ctrl:1
	v_add_f32_dpp v12, v12, v12 row_ror:8 row_mask:0xf bank_mask:0xf bound_ctrl:1
	v_pk_mul_f32 v[116:117], v[4:5], v[86:87]
	ds_read_b128 v[56:59], v7 offset:37536
	v_add_f32_dpp v10, v10, v10 row_ror:4 row_mask:0xf bank_mask:0xf bound_ctrl:1
	v_add_f32_dpp v12, v12, v12 row_ror:4 row_mask:0xf bank_mask:0xf bound_ctrl:1
	s_waitcnt lgkmcnt(10)
	v_pk_fma_f32 v[114:115], v[88:89], v[112:113], v[114:115] op_sel_hi:[1,0,1]
	ds_read_b128 v[36:39], v6 offset:33280
	v_add_f32_dpp v10, v10, v10 row_ror:2 row_mask:0xf bank_mask:0xf bound_ctrl:1
	v_add_f32_dpp v12, v12, v12 row_ror:2 row_mask:0xf bank_mask:0xf bound_ctrl:1
	v_pk_fma_f32 v[116:117], v[90:91], v[112:113], v[116:117] op_sel_hi:[1,0,1]
	ds_read_b128 v[40:43], v6 offset:33536
	v_add_f32_dpp v10, v10, v10 row_ror:1 row_mask:0xf bank_mask:0xf bound_ctrl:1
	v_add_f32_dpp v12, v12, v12 row_ror:1 row_mask:0xf bank_mask:0xf bound_ctrl:1
	v_fmac_f32_e32 v14, v112, v107
	ds_read2_b32 v[64:65], v120 offset0:192 offset1:208
	s_waitcnt lgkmcnt(9)
	v_pk_fma_f32 v[114:115], v[96:97], v[112:113], v[114:115] op_sel:[0,1,0] op_sel_hi:[1,1,1]
	v_fmac_f32_e32 v12, v112, v105
	v_pk_fma_f32 v[116:117], v[98:99], v[112:113], v[116:117] op_sel:[0,1,0] op_sel_hi:[1,1,1]
	ds_read_b128 v[48:51], v6 offset:34048
	v_fmac_f32_e32 v15, v112, v109
	v_pk_fma_f32 v[114:115], v[92:93], v[10:11], v[114:115] op_sel_hi:[1,0,1] neg_lo:[1,0,0] neg_hi:[1,0,0]
	v_fmac_f32_e32 v15, v113, v111
	ds_read_b128 v[44:47], v6 offset:33792
	v_pk_fma_f32 v[116:117], v[94:95], v[10:11], v[116:117] op_sel_hi:[1,0,1] neg_lo:[1,0,0] neg_hi:[1,0,0]
	v_fma_f32 v14, -v10, v106, v14
	v_fma_f32 v15, -v10, v108, v15
	ds_read_b128 v[52:55], v6 offset:34304
	v_fma_f32 v15, -v12, v110, v15
	v_pk_fma_f32 v[2:3], v[100:101], v[12:13], v[114:115] op_sel_hi:[1,0,1] neg_lo:[1,0,0] neg_hi:[1,0,0]
	v_pk_fma_f32 v[4:5], v[102:103], v[12:13], v[116:117] op_sel_hi:[1,0,1] neg_lo:[1,0,0] neg_hi:[1,0,0]
	ds_read_b128 v[60:63], v7 offset:37552
	ds_write2st64_b32 v9, v14, v15 offset0:104 offset1:108
	s_waitcnt lgkmcnt(8)
	v_pk_mul_f32 v[10:11], v[2:3], v[20:21] op_sel_hi:[0,1]
	ds_read_b128 v[68:71], v6 offset:34560
	v_pk_mul_f32 v[14:15], v[2:3], v[24:25] op_sel_hi:[0,1]
	v_pk_fma_f32 v[10:11], v[2:3], v[22:23], v[10:11] op_sel:[1,0,0] op_sel_hi:[1,1,1]
	v_pk_fma_f32 v[14:15], v[2:3], v[26:27], v[14:15] op_sel:[1,0,0] op_sel_hi:[1,1,1]
	ds_read_b128 v[76:79], v6 offset:35072
	v_pk_fma_f32 v[10:11], v[4:5], v[28:29], v[10:11] op_sel_hi:[0,1,1]
	v_pk_fma_f32 v[14:15], v[4:5], v[32:33], v[14:15] op_sel_hi:[0,1,1]
	v_pk_fma_f32 v[10:11], v[4:5], v[30:31], v[10:11] op_sel:[1,0,0] op_sel_hi:[1,1,1]
	ds_read_b128 v[72:75], v6 offset:34816
	v_pk_fma_f32 v[14:15], v[4:5], v[34:35], v[14:15] op_sel:[1,0,0] op_sel_hi:[1,1,1]
	v_fma_f32 v12, -v56, v10, v11
	s_waitcnt lgkmcnt(10)
	v_pk_mul_f32 v[114:115], v[2:3], v[36:37]
	ds_read_b128 v[80:83], v6 offset:35328
	v_add_f32_dpp v10, v10, v10 row_ror:8 row_mask:0xf bank_mask:0xf bound_ctrl:1
	v_add_f32_dpp v12, v12, v12 row_ror:8 row_mask:0xf bank_mask:0xf bound_ctrl:1
	v_pk_mul_f32 v[116:117], v[4:5], v[38:39]
	ds_read_b128 v[104:107], v7 offset:37584
	v_add_f32_dpp v10, v10, v10 row_ror:4 row_mask:0xf bank_mask:0xf bound_ctrl:1
	v_add_f32_dpp v12, v12, v12 row_ror:4 row_mask:0xf bank_mask:0xf bound_ctrl:1
	s_waitcnt lgkmcnt(10)
	v_pk_fma_f32 v[114:115], v[40:41], v[64:65], v[114:115] op_sel_hi:[1,0,1]
	ds_read_b128 v[84:87], v6 offset:35584
	v_add_f32_dpp v10, v10, v10 row_ror:2 row_mask:0xf bank_mask:0xf bound_ctrl:1
	v_add_f32_dpp v12, v12, v12 row_ror:2 row_mask:0xf bank_mask:0xf bound_ctrl:1
	v_pk_fma_f32 v[116:117], v[42:43], v[64:65], v[116:117] op_sel_hi:[1,0,1]
	ds_read_b128 v[88:91], v6 offset:35840
	v_add_f32_dpp v10, v10, v10 row_ror:1 row_mask:0xf bank_mask:0xf bound_ctrl:1
	v_add_f32_dpp v12, v12, v12 row_ror:1 row_mask:0xf bank_mask:0xf bound_ctrl:1
	v_fmac_f32_e32 v14, v64, v59
	ds_read2_b32 v[112:113], v120 offset0:224 offset1:240
	s_waitcnt lgkmcnt(9)
	v_pk_fma_f32 v[114:115], v[48:49], v[64:65], v[114:115] op_sel:[0,1,0] op_sel_hi:[1,1,1]
	v_fmac_f32_e32 v12, v64, v57
	v_pk_fma_f32 v[116:117], v[50:51], v[64:65], v[116:117] op_sel:[0,1,0] op_sel_hi:[1,1,1]
	ds_read_b128 v[96:99], v6 offset:36352
	v_fmac_f32_e32 v15, v64, v61
	v_pk_fma_f32 v[114:115], v[44:45], v[10:11], v[114:115] op_sel_hi:[1,0,1] neg_lo:[1,0,0] neg_hi:[1,0,0]
	v_fmac_f32_e32 v15, v65, v63
	ds_read_b128 v[92:95], v6 offset:36096
	v_pk_fma_f32 v[116:117], v[46:47], v[10:11], v[116:117] op_sel_hi:[1,0,1] neg_lo:[1,0,0] neg_hi:[1,0,0]
	v_fma_f32 v14, -v10, v58, v14
	v_fma_f32 v15, -v10, v60, v15
	ds_read_b128 v[100:103], v6 offset:36608
	v_fma_f32 v15, -v12, v62, v15
	v_pk_fma_f32 v[2:3], v[52:53], v[12:13], v[114:115] op_sel_hi:[1,0,1] neg_lo:[1,0,0] neg_hi:[1,0,0]
	v_pk_fma_f32 v[4:5], v[54:55], v[12:13], v[116:117] op_sel_hi:[1,0,1] neg_lo:[1,0,0] neg_hi:[1,0,0]
	ds_read_b128 v[108:111], v7 offset:37600
	ds_write2st64_b32 v9, v14, v15 offset0:112 offset1:116
	s_waitcnt lgkmcnt(8)
	v_pk_mul_f32 v[10:11], v[2:3], v[68:69] op_sel_hi:[0,1]
	v_pk_mul_f32 v[14:15], v[2:3], v[72:73] op_sel_hi:[0,1]
	v_pk_fma_f32 v[10:11], v[2:3], v[70:71], v[10:11] op_sel:[1,0,0] op_sel_hi:[1,1,1]
	v_pk_fma_f32 v[14:15], v[2:3], v[74:75], v[14:15] op_sel:[1,0,0] op_sel_hi:[1,1,1]
	v_pk_fma_f32 v[10:11], v[4:5], v[76:77], v[10:11] op_sel_hi:[0,1,1]
	v_pk_fma_f32 v[14:15], v[4:5], v[80:81], v[14:15] op_sel_hi:[0,1,1]
	v_pk_fma_f32 v[10:11], v[4:5], v[78:79], v[10:11] op_sel:[1,0,0] op_sel_hi:[1,1,1]
	v_pk_fma_f32 v[14:15], v[4:5], v[82:83], v[14:15] op_sel:[1,0,0] op_sel_hi:[1,1,1]
	v_fma_f32 v12, -v104, v10, v11
	s_waitcnt lgkmcnt(7)
	v_pk_mul_f32 v[114:115], v[2:3], v[84:85]
	v_add_f32_dpp v10, v10, v10 row_ror:8 row_mask:0xf bank_mask:0xf bound_ctrl:1
	v_add_f32_dpp v12, v12, v12 row_ror:8 row_mask:0xf bank_mask:0xf bound_ctrl:1
	v_pk_mul_f32 v[116:117], v[4:5], v[86:87]
	v_add_f32_dpp v10, v10, v10 row_ror:4 row_mask:0xf bank_mask:0xf bound_ctrl:1
	v_add_f32_dpp v12, v12, v12 row_ror:4 row_mask:0xf bank_mask:0xf bound_ctrl:1
	s_waitcnt lgkmcnt(5)
	v_pk_fma_f32 v[114:115], v[88:89], v[112:113], v[114:115] op_sel_hi:[1,0,1]
	v_add_f32_dpp v10, v10, v10 row_ror:2 row_mask:0xf bank_mask:0xf bound_ctrl:1
	v_add_f32_dpp v12, v12, v12 row_ror:2 row_mask:0xf bank_mask:0xf bound_ctrl:1
	v_pk_fma_f32 v[116:117], v[90:91], v[112:113], v[116:117] op_sel_hi:[1,0,1]
	v_add_f32_dpp v10, v10, v10 row_ror:1 row_mask:0xf bank_mask:0xf bound_ctrl:1
	v_add_f32_dpp v12, v12, v12 row_ror:1 row_mask:0xf bank_mask:0xf bound_ctrl:1
	v_fmac_f32_e32 v14, v112, v107
	s_waitcnt lgkmcnt(1)
	v_pk_fma_f32 v[114:115], v[96:97], v[112:113], v[114:115] op_sel:[0,1,0] op_sel_hi:[1,1,1]
	v_fmac_f32_e32 v12, v112, v105
	v_pk_fma_f32 v[116:117], v[98:99], v[112:113], v[116:117] op_sel:[0,1,0] op_sel_hi:[1,1,1]
	v_fmac_f32_e32 v15, v112, v109
	v_pk_fma_f32 v[114:115], v[92:93], v[10:11], v[114:115] op_sel_hi:[1,0,1] neg_lo:[1,0,0] neg_hi:[1,0,0]
	v_fmac_f32_e32 v15, v113, v111
	v_pk_fma_f32 v[116:117], v[94:95], v[10:11], v[116:117] op_sel_hi:[1,0,1] neg_lo:[1,0,0] neg_hi:[1,0,0]
	v_fma_f32 v14, -v10, v106, v14
	v_fma_f32 v15, -v10, v108, v15
	v_fma_f32 v15, -v12, v110, v15
	v_pk_fma_f32 v[2:3], v[100:101], v[12:13], v[114:115] op_sel_hi:[1,0,1] neg_lo:[1,0,0] neg_hi:[1,0,0]
	v_pk_fma_f32 v[4:5], v[102:103], v[12:13], v[116:117] op_sel_hi:[1,0,1] neg_lo:[1,0,0] neg_hi:[1,0,0]
	ds_write2st64_b32 v9, v14, v15 offset0:120 offset1:124
	v_add_u32_e32 v6, s1, v6
	v_add_u32_e32 v7, s1, v7
	v_add_u32_e32 v8, s1, v8
	v_add_u32_e32 v9, s1, v9
	v_add_u32_e32 v120, s1, v120
	s_sub_i32 s1, 0, s1
	s_add_i32 s0, s0, 1
	s_cmpk_eq_i32 s0, 0x200
	s_waitcnt lgkmcnt(0)
	s_barrier
	s_cbranch_scc0 .LBB0_652
	s_setprio 0
	s_mov_b64 s[0:1], 0
